# store_y: four gate loads of a tile issued together (+0/32/64/96 B) instead of load-wait-store ladder; silu via rcp
# speedup vs baseline: 1.0472x; 1.0021x over previous
; DI s16x4 pack4(f32x4 v) { bf4v b = __builtin_convertvector(v, bf4v); return __builtin_bit_cast(s16x4, b); }
; template <int O> DI float shx(float v) { return __builtin_bit_cast(float, shxi<O>(__builtin_bit_cast(int, v))); }
; DI void store_y(const f32x16& o0, const f32x16& o1, float inv, const bf16_t* G, bf16_t* Y, size_t row, int col0, int h) {
; #pragma unroll
;     for (int dd = 0; dd < 2; ++dd)
; #pragma unroll
;         for (int gp = 0; gp < 2; ++gp) {
;             const int g = 2 * gp;
;             const size_t off = row * DM + col0 + 32 * dd + 8 * (g + h);
;             const u32x4 gq = *(const u32x4*)(G + off);
;             const auto s0 = __builtin_amdgcn_permlane32_swap(gq.x, gq.z, false, false);
;             const auto s1 = __builtin_amdgcn_permlane32_swap(gq.y, gq.w, false, false);
;             const unsigned gg[2] = {s0[0], s1[0]}, gh[2] = {s0[1], s1[1]};
;             f32x4 tg, th;
; #pragma unroll
;             for (int e = 0; e < 4; ++e) {
;                 const float og = (dd == 0 ? o0[4 * g + e] : o1[4 * g + e]), oh = (dd == 0 ? o0[4 * g + 4 + e] : o1[4 * g + 4 + e]);
;                 const unsigned wg = gg[e >> 1], wh = gh[e >> 1];
;                 tg[e] = og * inv * bf2f((unsigned short)((e & 1) ? (wg >> 16) : (wg & 0xffffu)));
;                 th[e] = oh * inv * bf2f((unsigned short)((e & 1) ? (wh >> 16) : (wh & 0xffffu)));
;             }
;             const u32x2 yg = __builtin_bit_cast(u32x2, pack4(tg)), yh = __builtin_bit_cast(u32x2, pack4(th));
;             const auto t0 = __builtin_amdgcn_permlane32_swap(yg.x, yh.x, false, false);
;             const auto t1 = __builtin_amdgcn_permlane32_swap(yg.y, yh.y, false, false);
;             *(u32x4*)(Y + off) = (u32x4){t0[0], t1[0], t0[1], t1[1]};
;         }
; }
; template <int MODE>
; DI void attn_wg2_item(const bf16_t* Qm, const bf16_t* Km, const bf16_t* Vtm, const float* Fb, const float* KMPb, const bf16_t* G, bf16_t* Y, int bh, int qb2, int halfq, int mixer, float Mb, LAS unsigned char* lds, int tid, int wave, int lane) {
;     ...
;     lA += shx<32>(lA); lB += shx<32>(lB);
;     store_y(oA0, oA1, 1.0f / lA, G, Y, (size_t)(bh >> 3) * S + tA, mixer * 512 + (bh & 7) * 64, h);
.LBB0_353:
	s_andn2_b64 vcc, exec, s[48:49]
	s_waitcnt lgkmcnt(0)
	s_barrier
	s_cbranch_vccnz .LBB0_323
	v_mov_b32_e32 v0, v198
	v_mov_b32_e32 v2, v198
	s_nop 1
	v_permlane32_swap_b32_e32 v0, v2
	v_cndmask_b32_e64 v0, v0, v2, s[6:7]
	v_add_f32_e32 v0, v198, v0
	v_div_scale_f32 v2, s[0:1], v0, v0, 1.0
	v_rcp_f32_e32 v3, v2
	s_lshl_b32 s0, s83, 6
	s_or_b32 s4, s0, 0x600
	v_readlane_b32 s84, v254, 49
	s_waitcnt vmcnt(1)
	v_fma_f32 v6, -v2, v3, 1.0
	v_fmac_f32_e32 v3, v6, v3
	v_div_scale_f32 v6, vcc, 1.0, v0, 1.0
	v_mul_f32_e32 v7, v6, v3
	v_fma_f32 v8, -v2, v7, v6
	v_fmac_f32_e32 v7, v8, v3
	v_fma_f32 v2, -v2, v7, v6
	v_div_fmas_f32 v2, v2, v3, v7
	v_div_fixup_f32 v0, v2, v0, 1.0
	v_lshl_add_u64 v[2:3], v[168:169], 0, s[2:3]
	v_lshlrev_b64 v[2:3], 11, v[2:3]
	v_or_b32_e32 v2, s4, v2
	v_lshl_add_u64 v[6:7], v[2:3], 0, v[160:161]
	s_waitcnt vmcnt(0)
	v_lshlrev_b64 v[10:11], 1, v[6:7]
	v_readlane_b32 s85, v254, 50
	v_pk_mul_f32 v[14:15], v[64:65], v[0:1] op_sel_hi:[1,0]
	v_pk_mul_f32 v[64:65], v[66:67], v[0:1] op_sel_hi:[1,0]
	v_lshl_add_u64 v[6:7], s[84:85], 0, v[10:11]
	global_load_dwordx4 v[240:243], v[6:7], off offset:32
	global_load_dwordx4 v[244:247], v[6:7], off offset:64
	global_load_dwordx4 v[248:251], v[6:7], off offset:96
	global_load_dwordx4 v[6:9], v[6:7], off
	v_lshl_add_u64 v[10:11], s[94:95], 0, v[10:11]
	v_ashrrev_i32_e32 v163, 31, v162
	v_mov_b32_e32 v4, v175
	v_mov_b32_e32 v5, v175
	s_nop 1
	v_permlane32_swap_b32_e32 v4, v5
	s_mov_b64 s[0:1], 0
	s_andn2_b64 vcc, exec, s[10:11]
	s_mov_b64 s[62:63], 0
	s_waitcnt vmcnt(0)
	v_mov_b32_e32 v13, v8
	s_nop 1
	v_permlane32_swap_b32_e32 v6, v13
	v_mov_b32_e32 v80, v9
	s_nop 1
	v_permlane32_swap_b32_e32 v7, v80
	v_lshlrev_b32_e32 v8, 16, v6
	v_and_b32_e32 v9, 0xffff0000, v6
	v_lshlrev_b32_e32 v12, 16, v13
	v_pk_mul_f32 v[8:9], v[14:15], v[8:9]
	v_and_b32_e32 v13, 0xffff0000, v13
	v_pk_mul_f32 v[14:15], v[68:69], v[0:1] op_sel_hi:[1,0]
	v_lshlrev_b32_e32 v6, 16, v7
	v_and_b32_e32 v7, 0xffff0000, v7
	v_pk_mul_f32 v[12:13], v[14:15], v[12:13]
	v_lshlrev_b32_e32 v14, 16, v80
	v_pk_mul_f32 v[6:7], v[64:65], v[6:7]
	v_and_b32_e32 v15, 0xffff0000, v80
	v_pk_mul_f32 v[64:65], v[70:71], v[0:1] op_sel_hi:[1,0]
	v_cvt_pk_bf16_f32 v7, v6, v7
	v_pk_mul_f32 v[14:15], v[64:65], v[14:15]
	v_cvt_pk_bf16_f32 v6, v8, v9
	v_cvt_pk_bf16_f32 v9, v14, v15
	v_cvt_pk_bf16_f32 v8, v12, v13
	s_nop 1
	v_permlane32_swap_b32_e32 v6, v8
	v_permlane32_swap_b32_e32 v7, v9
	global_store_dwordx4 v[10:11], v[6:9], off
	v_pk_mul_f32 v[14:15], v[72:73], v[0:1] op_sel_hi:[1,0]
	v_pk_mul_f32 v[64:65], v[74:75], v[0:1] op_sel_hi:[1,0]
	v_lshl_add_u64 v[6:7], v[2:3], 0, v[162:163]
	v_lshlrev_b64 v[10:11], 1, v[6:7]
	v_lshl_add_u64 v[6:7], s[84:85], 0, v[10:11]
	v_lshl_add_u64 v[10:11], s[94:95], 0, v[10:11]
	v_or_b32_e32 v2, 32, v2
	v_mov_b32_e32 v6, v240
	v_mov_b32_e32 v7, v241
	v_mov_b32_e32 v8, v242
	v_mov_b32_e32 v9, v243
	v_mov_b32_e32 v13, v8
	s_nop 1
	v_permlane32_swap_b32_e32 v6, v13
	v_mov_b32_e32 v66, v9
	s_nop 1
	v_permlane32_swap_b32_e32 v7, v66
	v_lshlrev_b32_e32 v8, 16, v6
	v_and_b32_e32 v9, 0xffff0000, v6
	v_lshlrev_b32_e32 v12, 16, v13
	v_pk_mul_f32 v[8:9], v[14:15], v[8:9]
	v_and_b32_e32 v13, 0xffff0000, v13
	v_pk_mul_f32 v[14:15], v[76:77], v[0:1] op_sel_hi:[1,0]
	v_lshlrev_b32_e32 v6, 16, v7
	v_and_b32_e32 v7, 0xffff0000, v7
	v_pk_mul_f32 v[12:13], v[14:15], v[12:13]
	v_lshlrev_b32_e32 v14, 16, v66
	v_pk_mul_f32 v[6:7], v[64:65], v[6:7]
	v_and_b32_e32 v15, 0xffff0000, v66
	v_pk_mul_f32 v[64:65], v[78:79], v[0:1] op_sel_hi:[1,0]
	v_cvt_pk_bf16_f32 v7, v6, v7
	v_pk_mul_f32 v[14:15], v[64:65], v[14:15]
	v_cvt_pk_bf16_f32 v6, v8, v9
	v_cvt_pk_bf16_f32 v9, v14, v15
	v_cvt_pk_bf16_f32 v8, v12, v13
	s_nop 1
	v_permlane32_swap_b32_e32 v6, v8
	v_permlane32_swap_b32_e32 v7, v9
	global_store_dwordx4 v[10:11], v[6:9], off
	v_pk_mul_f32 v[14:15], v[48:49], v[0:1] op_sel_hi:[1,0]
	v_pk_mul_f32 v[48:49], v[50:51], v[0:1] op_sel_hi:[1,0]
	v_lshl_add_u64 v[6:7], v[2:3], 0, v[160:161]
	v_lshlrev_b64 v[10:11], 1, v[6:7]
	v_lshl_add_u64 v[6:7], s[84:85], 0, v[10:11]
	v_lshl_add_u64 v[2:3], v[2:3], 0, v[162:163]
	v_lshl_add_u64 v[10:11], s[94:95], 0, v[10:11]
	v_lshlrev_b64 v[2:3], 1, v[2:3]
	v_mov_b32_e32 v6, v244
	v_mov_b32_e32 v7, v245
	v_mov_b32_e32 v8, v246
	v_mov_b32_e32 v9, v247
	v_mov_b32_e32 v13, v8
	s_nop 1
	v_permlane32_swap_b32_e32 v6, v13
	v_mov_b32_e32 v64, v9
	s_nop 1
	v_permlane32_swap_b32_e32 v7, v64
	v_lshlrev_b32_e32 v8, 16, v6
	v_and_b32_e32 v9, 0xffff0000, v6
	v_lshlrev_b32_e32 v12, 16, v13
	v_pk_mul_f32 v[8:9], v[14:15], v[8:9]
	v_and_b32_e32 v13, 0xffff0000, v13
	v_pk_mul_f32 v[14:15], v[52:53], v[0:1] op_sel_hi:[1,0]
	v_lshlrev_b32_e32 v6, 16, v7
	v_and_b32_e32 v7, 0xffff0000, v7
	v_pk_mul_f32 v[12:13], v[14:15], v[12:13]
	v_lshlrev_b32_e32 v14, 16, v64
	v_pk_mul_f32 v[6:7], v[48:49], v[6:7]
	v_and_b32_e32 v15, 0xffff0000, v64
	v_pk_mul_f32 v[48:49], v[54:55], v[0:1] op_sel_hi:[1,0]
	v_cvt_pk_bf16_f32 v7, v6, v7
	v_pk_mul_f32 v[14:15], v[48:49], v[14:15]
	v_cvt_pk_bf16_f32 v6, v8, v9
	v_cvt_pk_bf16_f32 v9, v14, v15
	v_cvt_pk_bf16_f32 v8, v12, v13
	s_nop 1
	v_permlane32_swap_b32_e32 v6, v8
	v_permlane32_swap_b32_e32 v7, v9
	global_store_dwordx4 v[10:11], v[6:9], off
	v_pk_mul_f32 v[14:15], v[56:57], v[0:1] op_sel_hi:[1,0]
	s_nop 0
	v_lshl_add_u64 v[6:7], s[84:85], 0, v[2:3]
	v_lshl_add_u64 v[2:3], s[94:95], 0, v[2:3]
	v_mov_b32_e32 v6, v248
	v_mov_b32_e32 v7, v249
	v_mov_b32_e32 v8, v250
	v_mov_b32_e32 v9, v251
	v_mov_b32_e32 v10, v8
	s_nop 1
	v_permlane32_swap_b32_e32 v6, v10
	v_mov_b32_e32 v48, v9
	s_nop 1
	v_permlane32_swap_b32_e32 v7, v48
	v_lshlrev_b32_e32 v12, 16, v6
	v_and_b32_e32 v13, 0xffff0000, v6
	v_lshlrev_b32_e32 v8, 16, v10
	v_and_b32_e32 v9, 0xffff0000, v10
	v_pk_mul_f32 v[10:11], v[60:61], v[0:1] op_sel_hi:[1,0]
	v_pk_mul_f32 v[12:13], v[14:15], v[12:13]
	v_lshlrev_b32_e32 v6, 16, v7
	v_and_b32_e32 v7, 0xffff0000, v7
	v_pk_mul_f32 v[14:15], v[58:59], v[0:1] op_sel_hi:[1,0]
	v_pk_mul_f32 v[10:11], v[10:11], v[8:9]
	v_lshlrev_b32_e32 v8, 16, v48
	v_pk_mul_f32 v[6:7], v[14:15], v[6:7]
	v_and_b32_e32 v9, 0xffff0000, v48
	v_pk_mul_f32 v[14:15], v[62:63], v[0:1] op_sel_hi:[1,0]
	v_cvt_pk_bf16_f32 v7, v6, v7
	v_pk_mul_f32 v[8:9], v[14:15], v[8:9]
	v_cvt_pk_bf16_f32 v6, v12, v13
	v_cvt_pk_bf16_f32 v9, v8, v9
	v_cvt_pk_bf16_f32 v8, v10, v11
	s_nop 1
	v_permlane32_swap_b32_e32 v6, v8
	v_permlane32_swap_b32_e32 v7, v9
	global_store_dwordx4 v[2:3], v[6:9], off
	s_cbranch_vccnz .LBB0_357
; DI s16x4 pack4(f32x4 v) { bf4v b = __builtin_convertvector(v, bf4v); return __builtin_bit_cast(s16x4, b); }
; DI void store_y(const f32x16& o0, const f32x16& o1, float inv, const bf16_t* G, bf16_t* Y, size_t row, int col0, int h) {
; #pragma unroll
;     for (int dd = 0; dd < 2; ++dd)
; #pragma unroll
;         for (int gp = 0; gp < 2; ++gp) {
;             const int g = 2 * gp;
;             const size_t off = row * DM + col0 + 32 * dd + 8 * (g + h);
;             const u32x4 gq = *(const u32x4*)(G + off);
;             const auto s0 = __builtin_amdgcn_permlane32_swap(gq.x, gq.z, false, false);
;             const auto s1 = __builtin_amdgcn_permlane32_swap(gq.y, gq.w, false, false);
;             const unsigned gg[2] = {s0[0], s1[0]}, gh[2] = {s0[1], s1[1]};
;             f32x4 tg, th;
; #pragma unroll
;             for (int e = 0; e < 4; ++e) {
;                 const float og = (dd == 0 ? o0[4 * g + e] : o1[4 * g + e]), oh = (dd == 0 ? o0[4 * g + 4 + e] : o1[4 * g + 4 + e]);
;                 const unsigned wg = gg[e >> 1], wh = gh[e >> 1];
;                 tg[e] = og * inv * bf2f((unsigned short)((e & 1) ? (wg >> 16) : (wg & 0xffffu)));
;                 th[e] = oh * inv * bf2f((unsigned short)((e & 1) ? (wh >> 16) : (wh & 0xffffu)));
;             }
;             const u32x2 yg = __builtin_bit_cast(u32x2, pack4(tg)), yh = __builtin_bit_cast(u32x2, pack4(th));
;             const auto t0 = __builtin_amdgcn_permlane32_swap(yg.x, yh.x, false, false);
;             const auto t1 = __builtin_amdgcn_permlane32_swap(yg.y, yh.y, false, false);
;             *(u32x4*)(Y + off) = (u32x4){t0[0], t1[0], t0[1], t1[1]};
;         }
; }
; template <int MODE>
; DI void attn_wg2_item(const bf16_t* Qm, const bf16_t* Km, const bf16_t* Vtm, const float* Fb, const float* KMPb, const bf16_t* G, bf16_t* Y, int bh, int qb2, int halfq, int mixer, float Mb, LAS unsigned char* lds, int tid, int wave, int lane) {
;     ...
;     if (!halfq) store_y(oB0, oB1, 1.0f / lB, G, Y, (size_t)(bh >> 3) * S + tB, mixer * 512 + (bh & 7) * 64, h);
	v_lshl_add_u64 v[2:3], v[166:167], 0, s[2:3]
	v_lshlrev_b64 v[10:11], 11, v[2:3]
	v_or_b32_e32 v10, s4, v10
	v_lshl_add_u64 v[2:3], v[10:11], 0, v[160:161]
	v_lshlrev_b64 v[2:3], 1, v[2:3]
	v_lshl_add_u64 v[6:7], s[84:85], 0, v[2:3]
	global_load_dwordx4 v[240:243], v[6:7], off offset:32
	global_load_dwordx4 v[244:247], v[6:7], off offset:64
	global_load_dwordx4 v[248:251], v[6:7], off offset:96
	global_load_dwordx4 v[6:9], v[6:7], off
	v_cndmask_b32_e64 v0, v4, v5, s[6:7]
	v_add_f32_e32 v0, v175, v0
	v_div_scale_f32 v50, s[4:5], v0, v0, 1.0
	v_rcp_f32_e32 v52, v50
	v_lshl_add_u64 v[14:15], s[94:95], 0, v[2:3]
	v_div_scale_f32 v51, vcc, 1.0, v0, 1.0
	v_fma_f32 v2, -v50, v52, 1.0
	v_fmac_f32_e32 v52, v2, v52
	v_mul_f32_e32 v2, v51, v52
	v_fma_f32 v3, -v50, v2, v51
	v_fmac_f32_e32 v2, v3, v52
	v_fma_f32 v3, -v50, v2, v51
	v_div_fmas_f32 v2, v3, v52, v2
	v_lshl_add_u64 v[4:5], v[10:11], 0, v[162:163]
	v_div_fixup_f32 v0, v2, v0, 1.0
	v_lshlrev_b64 v[12:13], 1, v[4:5]
	v_pk_mul_f32 v[2:3], v[32:33], v[0:1] op_sel_hi:[1,0]
	v_pk_mul_f32 v[4:5], v[36:37], v[0:1] op_sel_hi:[1,0]
	v_pk_mul_f32 v[32:33], v[34:35], v[0:1] op_sel_hi:[1,0]
	v_pk_mul_f32 v[34:35], v[38:39], v[0:1] op_sel_hi:[1,0]
	v_lshl_add_u64 v[48:49], s[84:85], 0, v[12:13]
	v_or_b32_e32 v10, 32, v10
	s_mov_b64 s[62:63], -1
	s_waitcnt vmcnt(0)
	v_mov_b32_e32 v37, v8
	v_mov_b32_e32 v39, v9
	s_nop 0
	v_permlane32_swap_b32_e32 v6, v37
	v_permlane32_swap_b32_e32 v7, v39
	v_lshlrev_b32_e32 v8, 16, v6
	v_lshlrev_b32_e32 v36, 16, v37
	v_and_b32_e32 v9, 0xffff0000, v6
	v_and_b32_e32 v37, 0xffff0000, v37
	v_lshlrev_b32_e32 v6, 16, v7
	v_lshlrev_b32_e32 v38, 16, v39
	v_and_b32_e32 v7, 0xffff0000, v7
	v_and_b32_e32 v39, 0xffff0000, v39
	v_pk_mul_f32 v[8:9], v[2:3], v[8:9]
	v_pk_mul_f32 v[36:37], v[4:5], v[36:37]
	v_pk_mul_f32 v[2:3], v[32:33], v[6:7]
	v_pk_mul_f32 v[4:5], v[34:35], v[38:39]
	v_cvt_pk_bf16_f32 v3, v2, v3
	v_cvt_pk_bf16_f32 v2, v8, v9
	v_cvt_pk_bf16_f32 v5, v4, v5
	v_cvt_pk_bf16_f32 v4, v36, v37
	s_nop 1
	v_permlane32_swap_b32_e32 v2, v4
	v_permlane32_swap_b32_e32 v3, v5
	global_store_dwordx4 v[14:15], v[2:5], off
	v_pk_mul_f32 v[14:15], v[40:41], v[0:1] op_sel_hi:[1,0]
	v_pk_mul_f32 v[32:33], v[44:45], v[0:1] op_sel_hi:[1,0]
	v_pk_mul_f32 v[34:35], v[42:43], v[0:1] op_sel_hi:[1,0]
	v_pk_mul_f32 v[36:37], v[46:47], v[0:1] op_sel_hi:[1,0]
	v_lshl_add_u64 v[6:7], v[10:11], 0, v[160:161]
	v_lshl_add_u64 v[8:9], s[94:95], 0, v[12:13]
	v_lshlrev_b64 v[12:13], 1, v[6:7]
	v_lshl_add_u64 v[6:7], s[84:85], 0, v[12:13]
	v_mov_b32_e32 v2, v240
	v_mov_b32_e32 v3, v241
	v_mov_b32_e32 v4, v242
	v_mov_b32_e32 v5, v243
	v_mov_b32_e32 v39, v4
	v_mov_b32_e32 v41, v5
	s_nop 0
	v_permlane32_swap_b32_e32 v2, v39
	v_permlane32_swap_b32_e32 v3, v41
	v_lshlrev_b32_e32 v4, 16, v2
	v_lshlrev_b32_e32 v38, 16, v39
	v_and_b32_e32 v5, 0xffff0000, v2
	v_and_b32_e32 v39, 0xffff0000, v39
	v_lshlrev_b32_e32 v2, 16, v3
	v_lshlrev_b32_e32 v40, 16, v41
	v_and_b32_e32 v3, 0xffff0000, v3
	v_and_b32_e32 v41, 0xffff0000, v41
	v_pk_mul_f32 v[4:5], v[14:15], v[4:5]
	v_pk_mul_f32 v[14:15], v[32:33], v[38:39]
	v_pk_mul_f32 v[2:3], v[34:35], v[2:3]
	v_pk_mul_f32 v[32:33], v[36:37], v[40:41]
	v_cvt_pk_bf16_f32 v3, v2, v3
	v_cvt_pk_bf16_f32 v2, v4, v5
	v_cvt_pk_bf16_f32 v5, v32, v33
	v_cvt_pk_bf16_f32 v4, v14, v15
	s_nop 1
	v_permlane32_swap_b32_e32 v2, v4
	v_permlane32_swap_b32_e32 v3, v5
	global_store_dwordx4 v[8:9], v[2:5], off
	v_lshl_add_u64 v[6:7], v[10:11], 0, v[162:163]
	v_lshl_add_u64 v[10:11], s[94:95], 0, v[12:13]
	v_pk_mul_f32 v[12:13], v[16:17], v[0:1] op_sel_hi:[1,0]
	v_pk_mul_f32 v[14:15], v[20:21], v[0:1] op_sel_hi:[1,0]
	v_pk_mul_f32 v[16:17], v[18:19], v[0:1] op_sel_hi:[1,0]
	v_pk_mul_f32 v[18:19], v[22:23], v[0:1] op_sel_hi:[1,0]
	v_lshl_add_u64 v[8:9], v[6:7], 1, s[84:85]
	v_mov_b32_e32 v2, v244
	v_mov_b32_e32 v3, v245
	v_mov_b32_e32 v4, v246
	v_mov_b32_e32 v5, v247
	v_mov_b32_e32 v21, v4
	v_mov_b32_e32 v23, v5
	s_nop 0
	v_permlane32_swap_b32_e32 v2, v21
	v_permlane32_swap_b32_e32 v3, v23
	v_lshlrev_b32_e32 v4, 16, v2
	v_lshlrev_b32_e32 v20, 16, v21
	v_and_b32_e32 v5, 0xffff0000, v2
	v_and_b32_e32 v21, 0xffff0000, v21
	v_lshlrev_b32_e32 v2, 16, v3
	v_lshlrev_b32_e32 v22, 16, v23
	v_and_b32_e32 v3, 0xffff0000, v3
	v_and_b32_e32 v23, 0xffff0000, v23
	v_pk_mul_f32 v[4:5], v[12:13], v[4:5]
	v_pk_mul_f32 v[12:13], v[14:15], v[20:21]
	v_pk_mul_f32 v[2:3], v[16:17], v[2:3]
	v_pk_mul_f32 v[14:15], v[18:19], v[22:23]
	v_cvt_pk_bf16_f32 v3, v2, v3
	v_cvt_pk_bf16_f32 v2, v4, v5
	v_cvt_pk_bf16_f32 v5, v14, v15
	v_cvt_pk_bf16_f32 v4, v12, v13
	s_nop 1
	v_permlane32_swap_b32_e32 v2, v4
	v_permlane32_swap_b32_e32 v3, v5
	global_store_dwordx4 v[10:11], v[2:5], off
	v_pk_mul_f32 v[8:9], v[28:29], v[0:1] op_sel_hi:[1,0]
	v_pk_mul_f32 v[10:11], v[24:25], v[0:1] op_sel_hi:[1,0]
	v_pk_mul_f32 v[12:13], v[26:27], v[0:1] op_sel_hi:[1,0]
	v_pk_mul_f32 v[14:15], v[30:31], v[0:1] op_sel_hi:[1,0]
	v_mov_b32_e32 v2, v248
	v_mov_b32_e32 v3, v249
	v_mov_b32_e32 v4, v250
	v_mov_b32_e32 v5, v251
	v_mov_b32_e32 v0, v4
	v_mov_b32_e32 v17, v5
	s_nop 0
	v_permlane32_swap_b32_e32 v2, v0
	v_permlane32_swap_b32_e32 v3, v17
	v_lshlrev_b32_e32 v4, 16, v0
	v_and_b32_e32 v5, 0xffff0000, v0
	v_lshlrev_b32_e32 v16, 16, v17
	v_lshlrev_b32_e32 v18, 16, v2
	v_and_b32_e32 v19, 0xffff0000, v2
	v_lshlrev_b32_e32 v2, 16, v3
	v_and_b32_e32 v3, 0xffff0000, v3
	v_and_b32_e32 v17, 0xffff0000, v17
	v_pk_mul_f32 v[8:9], v[8:9], v[4:5]
	v_pk_mul_f32 v[4:5], v[10:11], v[18:19]
	v_pk_mul_f32 v[2:3], v[12:13], v[2:3]
	v_pk_mul_f32 v[10:11], v[14:15], v[16:17]
	v_cvt_pk_bf16_f32 v3, v2, v3
	v_cvt_pk_bf16_f32 v2, v4, v5
	v_cvt_pk_bf16_f32 v5, v10, v11
	v_cvt_pk_bf16_f32 v4, v8, v9
	s_nop 1
	v_permlane32_swap_b32_e32 v2, v4
	v_permlane32_swap_b32_e32 v3, v5
	s_branch .LBB0_357

; DI s16x4 pack4(f32x4 v) { bf4v b = __builtin_convertvector(v, bf4v); return __builtin_bit_cast(s16x4, b); }
; template <int O> DI float shx(float v) { return __builtin_bit_cast(float, shxi<O>(__builtin_bit_cast(int, v))); }
; DI void store_y(const f32x16& o0, const f32x16& o1, float inv, const bf16_t* G, bf16_t* Y, size_t row, int col0, int h) {
; #pragma unroll
;     for (int dd = 0; dd < 2; ++dd)
; #pragma unroll
;         for (int gp = 0; gp < 2; ++gp) {
;             const int g = 2 * gp;
;             const size_t off = row * DM + col0 + 32 * dd + 8 * (g + h);
;             const u32x4 gq = *(const u32x4*)(G + off);
;             const auto s0 = __builtin_amdgcn_permlane32_swap(gq.x, gq.z, false, false);
;             const auto s1 = __builtin_amdgcn_permlane32_swap(gq.y, gq.w, false, false);
;             const unsigned gg[2] = {s0[0], s1[0]}, gh[2] = {s0[1], s1[1]};
;             f32x4 tg, th;
; #pragma unroll
;             for (int e = 0; e < 4; ++e) {
;                 const float og = (dd == 0 ? o0[4 * g + e] : o1[4 * g + e]), oh = (dd == 0 ? o0[4 * g + 4 + e] : o1[4 * g + 4 + e]);
;                 const unsigned wg = gg[e >> 1], wh = gh[e >> 1];
;                 tg[e] = og * inv * bf2f((unsigned short)((e & 1) ? (wg >> 16) : (wg & 0xffffu)));
;                 th[e] = oh * inv * bf2f((unsigned short)((e & 1) ? (wh >> 16) : (wh & 0xffffu)));
;             }
;             const u32x2 yg = __builtin_bit_cast(u32x2, pack4(tg)), yh = __builtin_bit_cast(u32x2, pack4(th));
;             const auto t0 = __builtin_amdgcn_permlane32_swap(yg.x, yh.x, false, false);
;             const auto t1 = __builtin_amdgcn_permlane32_swap(yg.y, yh.y, false, false);
;             *(u32x4*)(Y + off) = (u32x4){t0[0], t1[0], t0[1], t1[1]};
;         }
; }
; template <int MODE>
; DI void attn_wg2_item(const bf16_t* Qm, const bf16_t* Km, const bf16_t* Vtm, const float* Fb, const float* KMPb, const bf16_t* G, bf16_t* Y, int bh, int qb2, int halfq, int mixer, float Mb, LAS unsigned char* lds, int tid, int wave, int lane) {
;     ...
;     lA += shx<32>(lA); lB += shx<32>(lB);
;     store_y(oA0, oA1, 1.0f / lA, G, Y, (size_t)(bh >> 3) * S + tA, mixer * 512 + (bh & 7) * 64, h);
.LBB0_417:
	v_mov_b32_e32 v0, v186
	s_waitcnt vmcnt(0)
	v_mov_b32_e32 v2, v186
	s_nop 1
	v_permlane32_swap_b32_e32 v0, v2
	v_cndmask_b32_e64 v0, v0, v2, s[6:7]
	v_add_f32_e32 v0, v186, v0
	v_div_scale_f32 v2, s[0:1], v0, v0, 1.0
	v_rcp_f32_e32 v3, v2
	s_lshl_b32 s0, s83, 6
	s_and_b32 s0, s0, 0x1c0
	s_bitset1_b32 s0, 10
	v_fma_f32 v6, -v2, v3, 1.0
	v_fmac_f32_e32 v3, v6, v3
	v_div_scale_f32 v6, vcc, 1.0, v0, 1.0
	v_mul_f32_e32 v7, v6, v3
	v_fma_f32 v8, -v2, v7, v6
	v_fmac_f32_e32 v7, v8, v3
	v_fma_f32 v2, -v2, v7, v6
	v_div_fmas_f32 v2, v2, v3, v7
	v_div_fixup_f32 v0, v2, v0, 1.0
	v_lshl_add_u64 v[2:3], v[160:161], 0, s[2:3]
	v_lshlrev_b64 v[2:3], 11, v[2:3]
	v_or_b32_e32 v2, s0, v2
	v_lshl_add_u64 v[6:7], v[2:3], 0, v[156:157]
	v_readlane_b32 s84, v254, 49
	v_lshlrev_b64 v[10:11], 1, v[6:7]
	v_readlane_b32 s85, v254, 50
	v_pk_mul_f32 v[14:15], v[64:65], v[0:1] op_sel_hi:[1,0]
	v_pk_mul_f32 v[64:65], v[66:67], v[0:1] op_sel_hi:[1,0]
	v_lshl_add_u64 v[6:7], s[84:85], 0, v[10:11]
	global_load_dwordx4 v[240:243], v[6:7], off offset:32
	global_load_dwordx4 v[244:247], v[6:7], off offset:64
	global_load_dwordx4 v[248:251], v[6:7], off offset:96
	global_load_dwordx4 v[6:9], v[6:7], off
	v_lshl_add_u64 v[10:11], s[94:95], 0, v[10:11]
	v_ashrrev_i32_e32 v163, 31, v162
	v_mov_b32_e32 v4, v170
	v_mov_b32_e32 v5, v170
	s_nop 1
	v_permlane32_swap_b32_e32 v4, v5
	s_andn2_b64 vcc, exec, s[10:11]
	s_waitcnt vmcnt(0)
	v_mov_b32_e32 v13, v8
	s_nop 1
	v_permlane32_swap_b32_e32 v6, v13
	v_mov_b32_e32 v80, v9
	s_nop 1
	v_permlane32_swap_b32_e32 v7, v80
	v_lshlrev_b32_e32 v8, 16, v6
	v_and_b32_e32 v9, 0xffff0000, v6
	v_lshlrev_b32_e32 v12, 16, v13
	v_pk_mul_f32 v[8:9], v[14:15], v[8:9]
	v_and_b32_e32 v13, 0xffff0000, v13
	v_pk_mul_f32 v[14:15], v[68:69], v[0:1] op_sel_hi:[1,0]
	v_lshlrev_b32_e32 v6, 16, v7
	v_and_b32_e32 v7, 0xffff0000, v7
	v_pk_mul_f32 v[12:13], v[14:15], v[12:13]
	v_lshlrev_b32_e32 v14, 16, v80
	v_pk_mul_f32 v[6:7], v[64:65], v[6:7]
	v_and_b32_e32 v15, 0xffff0000, v80
	v_pk_mul_f32 v[64:65], v[70:71], v[0:1] op_sel_hi:[1,0]
	v_cvt_pk_bf16_f32 v7, v6, v7
	v_pk_mul_f32 v[14:15], v[64:65], v[14:15]
	v_cvt_pk_bf16_f32 v6, v8, v9
	v_cvt_pk_bf16_f32 v9, v14, v15
	v_cvt_pk_bf16_f32 v8, v12, v13
	s_nop 1
	v_permlane32_swap_b32_e32 v6, v8
	v_permlane32_swap_b32_e32 v7, v9
	global_store_dwordx4 v[10:11], v[6:9], off
	v_pk_mul_f32 v[14:15], v[72:73], v[0:1] op_sel_hi:[1,0]
	v_pk_mul_f32 v[64:65], v[74:75], v[0:1] op_sel_hi:[1,0]
	v_lshl_add_u64 v[6:7], v[2:3], 0, v[162:163]
	v_lshlrev_b64 v[10:11], 1, v[6:7]
	v_lshl_add_u64 v[6:7], s[84:85], 0, v[10:11]
	v_lshl_add_u64 v[10:11], s[94:95], 0, v[10:11]
	v_or_b32_e32 v2, 32, v2
	v_mov_b32_e32 v6, v240
	v_mov_b32_e32 v7, v241
	v_mov_b32_e32 v8, v242
	v_mov_b32_e32 v9, v243
	v_mov_b32_e32 v13, v8
	s_nop 1
	v_permlane32_swap_b32_e32 v6, v13
	v_mov_b32_e32 v66, v9
	s_nop 1
	v_permlane32_swap_b32_e32 v7, v66
	v_lshlrev_b32_e32 v8, 16, v6
	v_and_b32_e32 v9, 0xffff0000, v6
	v_lshlrev_b32_e32 v12, 16, v13
	v_pk_mul_f32 v[8:9], v[14:15], v[8:9]
	v_and_b32_e32 v13, 0xffff0000, v13
	v_pk_mul_f32 v[14:15], v[76:77], v[0:1] op_sel_hi:[1,0]
	v_lshlrev_b32_e32 v6, 16, v7
	v_and_b32_e32 v7, 0xffff0000, v7
	v_pk_mul_f32 v[12:13], v[14:15], v[12:13]
	v_lshlrev_b32_e32 v14, 16, v66
	v_pk_mul_f32 v[6:7], v[64:65], v[6:7]
	v_and_b32_e32 v15, 0xffff0000, v66
	v_pk_mul_f32 v[64:65], v[78:79], v[0:1] op_sel_hi:[1,0]
	v_cvt_pk_bf16_f32 v7, v6, v7
	v_pk_mul_f32 v[14:15], v[64:65], v[14:15]
	v_cvt_pk_bf16_f32 v6, v8, v9
	v_cvt_pk_bf16_f32 v9, v14, v15
	v_cvt_pk_bf16_f32 v8, v12, v13
	s_nop 1
	v_permlane32_swap_b32_e32 v6, v8
	v_permlane32_swap_b32_e32 v7, v9
	global_store_dwordx4 v[10:11], v[6:9], off
	v_pk_mul_f32 v[14:15], v[48:49], v[0:1] op_sel_hi:[1,0]
	v_pk_mul_f32 v[48:49], v[50:51], v[0:1] op_sel_hi:[1,0]
	v_lshl_add_u64 v[6:7], v[2:3], 0, v[156:157]
	v_lshlrev_b64 v[10:11], 1, v[6:7]
	v_lshl_add_u64 v[6:7], s[84:85], 0, v[10:11]
	v_lshl_add_u64 v[2:3], v[2:3], 0, v[162:163]
	v_lshl_add_u64 v[10:11], s[94:95], 0, v[10:11]
	v_lshlrev_b64 v[2:3], 1, v[2:3]
	v_mov_b32_e32 v6, v244
	v_mov_b32_e32 v7, v245
	v_mov_b32_e32 v8, v246
	v_mov_b32_e32 v9, v247
	v_mov_b32_e32 v13, v8
	s_nop 1
	v_permlane32_swap_b32_e32 v6, v13
	v_mov_b32_e32 v64, v9
	s_nop 1
	v_permlane32_swap_b32_e32 v7, v64
	v_lshlrev_b32_e32 v8, 16, v6
	v_and_b32_e32 v9, 0xffff0000, v6
	v_lshlrev_b32_e32 v12, 16, v13
	v_pk_mul_f32 v[8:9], v[14:15], v[8:9]
	v_and_b32_e32 v13, 0xffff0000, v13
	v_pk_mul_f32 v[14:15], v[52:53], v[0:1] op_sel_hi:[1,0]
	v_lshlrev_b32_e32 v6, 16, v7
	v_and_b32_e32 v7, 0xffff0000, v7
	v_pk_mul_f32 v[12:13], v[14:15], v[12:13]
	v_lshlrev_b32_e32 v14, 16, v64
	v_pk_mul_f32 v[6:7], v[48:49], v[6:7]
	v_and_b32_e32 v15, 0xffff0000, v64
	v_pk_mul_f32 v[48:49], v[54:55], v[0:1] op_sel_hi:[1,0]
	v_cvt_pk_bf16_f32 v7, v6, v7
	v_pk_mul_f32 v[14:15], v[48:49], v[14:15]
	v_cvt_pk_bf16_f32 v6, v8, v9
	v_cvt_pk_bf16_f32 v9, v14, v15
	v_cvt_pk_bf16_f32 v8, v12, v13
	s_nop 1
	v_permlane32_swap_b32_e32 v6, v8
	v_permlane32_swap_b32_e32 v7, v9
	global_store_dwordx4 v[10:11], v[6:9], off
	v_pk_mul_f32 v[14:15], v[56:57], v[0:1] op_sel_hi:[1,0]
	s_nop 0
	v_lshl_add_u64 v[6:7], s[84:85], 0, v[2:3]
	v_lshl_add_u64 v[2:3], s[94:95], 0, v[2:3]
	v_mov_b32_e32 v6, v248
	v_mov_b32_e32 v7, v249
	v_mov_b32_e32 v8, v250
	v_mov_b32_e32 v9, v251
	v_mov_b32_e32 v10, v8
	s_nop 1
	v_permlane32_swap_b32_e32 v6, v10
	v_mov_b32_e32 v48, v9
	s_nop 1
	v_permlane32_swap_b32_e32 v7, v48
	v_lshlrev_b32_e32 v12, 16, v6
	v_and_b32_e32 v13, 0xffff0000, v6
	v_lshlrev_b32_e32 v8, 16, v10
	v_and_b32_e32 v9, 0xffff0000, v10
	v_pk_mul_f32 v[10:11], v[60:61], v[0:1] op_sel_hi:[1,0]
	v_pk_mul_f32 v[12:13], v[14:15], v[12:13]
	v_lshlrev_b32_e32 v6, 16, v7
	v_and_b32_e32 v7, 0xffff0000, v7
	v_pk_mul_f32 v[14:15], v[58:59], v[0:1] op_sel_hi:[1,0]
	v_pk_mul_f32 v[10:11], v[10:11], v[8:9]
	v_lshlrev_b32_e32 v8, 16, v48
	v_pk_mul_f32 v[6:7], v[14:15], v[6:7]
	v_and_b32_e32 v9, 0xffff0000, v48
	v_pk_mul_f32 v[14:15], v[62:63], v[0:1] op_sel_hi:[1,0]
	v_cvt_pk_bf16_f32 v7, v6, v7
	v_pk_mul_f32 v[8:9], v[14:15], v[8:9]
	v_cvt_pk_bf16_f32 v6, v12, v13
	v_cvt_pk_bf16_f32 v9, v8, v9
	v_cvt_pk_bf16_f32 v8, v10, v11
	s_nop 1
	v_permlane32_swap_b32_e32 v6, v8
	v_permlane32_swap_b32_e32 v7, v9
	global_store_dwordx4 v[2:3], v[6:9], off
	s_cbranch_vccnz .LBB0_419
; DI s16x4 pack4(f32x4 v) { bf4v b = __builtin_convertvector(v, bf4v); return __builtin_bit_cast(s16x4, b); }
; DI void store_y(const f32x16& o0, const f32x16& o1, float inv, const bf16_t* G, bf16_t* Y, size_t row, int col0, int h) {
; #pragma unroll
;     for (int dd = 0; dd < 2; ++dd)
; #pragma unroll
;         for (int gp = 0; gp < 2; ++gp) {
;             const int g = 2 * gp;
;             const size_t off = row * DM + col0 + 32 * dd + 8 * (g + h);
;             const u32x4 gq = *(const u32x4*)(G + off);
;             const auto s0 = __builtin_amdgcn_permlane32_swap(gq.x, gq.z, false, false);
;             const auto s1 = __builtin_amdgcn_permlane32_swap(gq.y, gq.w, false, false);
;             const unsigned gg[2] = {s0[0], s1[0]}, gh[2] = {s0[1], s1[1]};
;             f32x4 tg, th;
; #pragma unroll
;             for (int e = 0; e < 4; ++e) {
;                 const float og = (dd == 0 ? o0[4 * g + e] : o1[4 * g + e]), oh = (dd == 0 ? o0[4 * g + 4 + e] : o1[4 * g + 4 + e]);
;                 const unsigned wg = gg[e >> 1], wh = gh[e >> 1];
;                 tg[e] = og * inv * bf2f((unsigned short)((e & 1) ? (wg >> 16) : (wg & 0xffffu)));
;                 th[e] = oh * inv * bf2f((unsigned short)((e & 1) ? (wh >> 16) : (wh & 0xffffu)));
;             }
;             const u32x2 yg = __builtin_bit_cast(u32x2, pack4(tg)), yh = __builtin_bit_cast(u32x2, pack4(th));
;             const auto t0 = __builtin_amdgcn_permlane32_swap(yg.x, yh.x, false, false);
;             const auto t1 = __builtin_amdgcn_permlane32_swap(yg.y, yh.y, false, false);
;             *(u32x4*)(Y + off) = (u32x4){t0[0], t1[0], t0[1], t1[1]};
;         }
; }
; template <int MODE>
; DI void attn_wg2_item(const bf16_t* Qm, const bf16_t* Km, const bf16_t* Vtm, const float* Fb, const float* KMPb, const bf16_t* G, bf16_t* Y, int bh, int qb2, int halfq, int mixer, float Mb, LAS unsigned char* lds, int tid, int wave, int lane) {
;     ...
;     if (!halfq) store_y(oB0, oB1, 1.0f / lB, G, Y, (size_t)(bh >> 3) * S + tB, mixer * 512 + (bh & 7) * 64, h);
	v_lshl_add_u64 v[2:3], v[158:159], 0, s[2:3]
	v_lshlrev_b64 v[10:11], 11, v[2:3]
	v_or_b32_e32 v10, s0, v10
	v_lshl_add_u64 v[2:3], v[10:11], 0, v[156:157]
	v_lshlrev_b64 v[2:3], 1, v[2:3]
	v_lshl_add_u64 v[6:7], s[84:85], 0, v[2:3]
	global_load_dwordx4 v[240:243], v[6:7], off offset:32
	global_load_dwordx4 v[244:247], v[6:7], off offset:64
	global_load_dwordx4 v[248:251], v[6:7], off offset:96
	global_load_dwordx4 v[6:9], v[6:7], off
	v_cndmask_b32_e64 v0, v4, v5, s[6:7]
	v_add_f32_e32 v0, v170, v0
	v_div_scale_f32 v50, s[0:1], v0, v0, 1.0
	v_rcp_f32_e32 v52, v50
	v_lshl_add_u64 v[14:15], s[94:95], 0, v[2:3]
	v_div_scale_f32 v51, vcc, 1.0, v0, 1.0
	v_fma_f32 v2, -v50, v52, 1.0
	v_fmac_f32_e32 v52, v2, v52
	v_mul_f32_e32 v2, v51, v52
	v_fma_f32 v3, -v50, v2, v51
	v_fmac_f32_e32 v2, v3, v52
	v_fma_f32 v3, -v50, v2, v51
	v_div_fmas_f32 v2, v3, v52, v2
	v_lshl_add_u64 v[4:5], v[10:11], 0, v[162:163]
	v_div_fixup_f32 v0, v2, v0, 1.0
	v_lshlrev_b64 v[12:13], 1, v[4:5]
	v_pk_mul_f32 v[2:3], v[32:33], v[0:1] op_sel_hi:[1,0]
	v_pk_mul_f32 v[4:5], v[36:37], v[0:1] op_sel_hi:[1,0]
	v_pk_mul_f32 v[32:33], v[34:35], v[0:1] op_sel_hi:[1,0]
	v_pk_mul_f32 v[34:35], v[38:39], v[0:1] op_sel_hi:[1,0]
	v_lshl_add_u64 v[48:49], s[84:85], 0, v[12:13]
	v_or_b32_e32 v10, 32, v10
	s_mov_b64 s[62:63], -1
	s_waitcnt vmcnt(0)
	v_mov_b32_e32 v37, v8
	v_mov_b32_e32 v39, v9
	s_nop 0
	v_permlane32_swap_b32_e32 v6, v37
	v_permlane32_swap_b32_e32 v7, v39
	v_lshlrev_b32_e32 v8, 16, v6
	v_lshlrev_b32_e32 v36, 16, v37
	v_and_b32_e32 v9, 0xffff0000, v6
	v_and_b32_e32 v37, 0xffff0000, v37
	v_lshlrev_b32_e32 v6, 16, v7
	v_lshlrev_b32_e32 v38, 16, v39
	v_and_b32_e32 v7, 0xffff0000, v7
	v_and_b32_e32 v39, 0xffff0000, v39
	v_pk_mul_f32 v[8:9], v[2:3], v[8:9]
	v_pk_mul_f32 v[36:37], v[4:5], v[36:37]
	v_pk_mul_f32 v[2:3], v[32:33], v[6:7]
	v_pk_mul_f32 v[4:5], v[34:35], v[38:39]
	v_cvt_pk_bf16_f32 v3, v2, v3
	v_cvt_pk_bf16_f32 v2, v8, v9
	v_cvt_pk_bf16_f32 v5, v4, v5
	v_cvt_pk_bf16_f32 v4, v36, v37
	s_nop 1
	v_permlane32_swap_b32_e32 v2, v4
	v_permlane32_swap_b32_e32 v3, v5
	global_store_dwordx4 v[14:15], v[2:5], off
	v_pk_mul_f32 v[14:15], v[40:41], v[0:1] op_sel_hi:[1,0]
	v_pk_mul_f32 v[32:33], v[44:45], v[0:1] op_sel_hi:[1,0]
	v_pk_mul_f32 v[34:35], v[42:43], v[0:1] op_sel_hi:[1,0]
	v_pk_mul_f32 v[36:37], v[46:47], v[0:1] op_sel_hi:[1,0]
	v_lshl_add_u64 v[6:7], v[10:11], 0, v[156:157]
	v_lshl_add_u64 v[8:9], s[94:95], 0, v[12:13]
	v_lshlrev_b64 v[12:13], 1, v[6:7]
	v_lshl_add_u64 v[6:7], s[84:85], 0, v[12:13]
	v_mov_b32_e32 v2, v240
	v_mov_b32_e32 v3, v241
	v_mov_b32_e32 v4, v242
	v_mov_b32_e32 v5, v243
	v_mov_b32_e32 v39, v4
	v_mov_b32_e32 v41, v5
	s_nop 0
	v_permlane32_swap_b32_e32 v2, v39
	v_permlane32_swap_b32_e32 v3, v41
	v_lshlrev_b32_e32 v4, 16, v2
	v_lshlrev_b32_e32 v38, 16, v39
	v_and_b32_e32 v5, 0xffff0000, v2
	v_and_b32_e32 v39, 0xffff0000, v39
	v_lshlrev_b32_e32 v2, 16, v3
	v_lshlrev_b32_e32 v40, 16, v41
	v_and_b32_e32 v3, 0xffff0000, v3
	v_and_b32_e32 v41, 0xffff0000, v41
	v_pk_mul_f32 v[4:5], v[14:15], v[4:5]
	v_pk_mul_f32 v[14:15], v[32:33], v[38:39]
	v_pk_mul_f32 v[2:3], v[34:35], v[2:3]
	v_pk_mul_f32 v[32:33], v[36:37], v[40:41]
	v_cvt_pk_bf16_f32 v3, v2, v3
	v_cvt_pk_bf16_f32 v2, v4, v5
	v_cvt_pk_bf16_f32 v5, v32, v33
	v_cvt_pk_bf16_f32 v4, v14, v15
	s_nop 1
	v_permlane32_swap_b32_e32 v2, v4
	v_permlane32_swap_b32_e32 v3, v5
	global_store_dwordx4 v[8:9], v[2:5], off
	v_lshl_add_u64 v[6:7], v[10:11], 0, v[162:163]
	v_lshl_add_u64 v[10:11], s[94:95], 0, v[12:13]
	v_pk_mul_f32 v[12:13], v[16:17], v[0:1] op_sel_hi:[1,0]
	v_pk_mul_f32 v[14:15], v[20:21], v[0:1] op_sel_hi:[1,0]
	v_pk_mul_f32 v[16:17], v[18:19], v[0:1] op_sel_hi:[1,0]
	v_pk_mul_f32 v[18:19], v[22:23], v[0:1] op_sel_hi:[1,0]
	v_lshl_add_u64 v[8:9], v[6:7], 1, s[84:85]
	v_mov_b32_e32 v2, v244
	v_mov_b32_e32 v3, v245
	v_mov_b32_e32 v4, v246
	v_mov_b32_e32 v5, v247
	v_mov_b32_e32 v21, v4
	v_mov_b32_e32 v23, v5
	s_nop 0
	v_permlane32_swap_b32_e32 v2, v21
	v_permlane32_swap_b32_e32 v3, v23
	v_lshlrev_b32_e32 v4, 16, v2
	v_lshlrev_b32_e32 v20, 16, v21
	v_and_b32_e32 v5, 0xffff0000, v2
	v_and_b32_e32 v21, 0xffff0000, v21
	v_lshlrev_b32_e32 v2, 16, v3
	v_lshlrev_b32_e32 v22, 16, v23
	v_and_b32_e32 v3, 0xffff0000, v3
	v_and_b32_e32 v23, 0xffff0000, v23
	v_pk_mul_f32 v[4:5], v[12:13], v[4:5]
	v_pk_mul_f32 v[12:13], v[14:15], v[20:21]
	v_pk_mul_f32 v[2:3], v[16:17], v[2:3]
	v_pk_mul_f32 v[14:15], v[18:19], v[22:23]
	v_cvt_pk_bf16_f32 v3, v2, v3
	v_cvt_pk_bf16_f32 v2, v4, v5
	v_cvt_pk_bf16_f32 v5, v14, v15
	v_cvt_pk_bf16_f32 v4, v12, v13
	s_nop 1
	v_permlane32_swap_b32_e32 v2, v4
	v_permlane32_swap_b32_e32 v3, v5
	global_store_dwordx4 v[10:11], v[2:5], off
	v_pk_mul_f32 v[8:9], v[28:29], v[0:1] op_sel_hi:[1,0]
	v_pk_mul_f32 v[10:11], v[24:25], v[0:1] op_sel_hi:[1,0]
	v_pk_mul_f32 v[12:13], v[26:27], v[0:1] op_sel_hi:[1,0]
	v_pk_mul_f32 v[14:15], v[30:31], v[0:1] op_sel_hi:[1,0]
	v_mov_b32_e32 v2, v248
	v_mov_b32_e32 v3, v249
	v_mov_b32_e32 v4, v250
	v_mov_b32_e32 v5, v251
	v_mov_b32_e32 v0, v4
	v_mov_b32_e32 v17, v5
	s_nop 0
	v_permlane32_swap_b32_e32 v2, v0
	v_permlane32_swap_b32_e32 v3, v17
	v_lshlrev_b32_e32 v4, 16, v0
	v_and_b32_e32 v5, 0xffff0000, v0
	v_lshlrev_b32_e32 v16, 16, v17
	v_lshlrev_b32_e32 v18, 16, v2
	v_and_b32_e32 v19, 0xffff0000, v2
	v_lshlrev_b32_e32 v2, 16, v3
	v_and_b32_e32 v3, 0xffff0000, v3
	v_and_b32_e32 v17, 0xffff0000, v17
	v_pk_mul_f32 v[8:9], v[8:9], v[4:5]
	v_pk_mul_f32 v[4:5], v[10:11], v[18:19]
	v_pk_mul_f32 v[2:3], v[12:13], v[2:3]
	v_pk_mul_f32 v[10:11], v[14:15], v[16:17]
	v_cvt_pk_bf16_f32 v3, v2, v3
	v_cvt_pk_bf16_f32 v2, v4, v5
	v_cvt_pk_bf16_f32 v5, v10, v11
	v_cvt_pk_bf16_f32 v4, v8, v9
	s_nop 1
	v_permlane32_swap_b32_e32 v2, v4
	v_permlane32_swap_b32_e32 v3, v5

; DI s16x4 pack4(f32x4 v) { bf4v b = __builtin_convertvector(v, bf4v); return __builtin_bit_cast(s16x4, b); }
; DI void store_y(const f32x16& o0, const f32x16& o1, float inv, const bf16_t* G, bf16_t* Y, size_t row, int col0, int h) {
; #pragma unroll
;     for (int dd = 0; dd < 2; ++dd)
; #pragma unroll
;         for (int gp = 0; gp < 2; ++gp) {
;             const int g = 2 * gp;
;             const size_t off = row * DM + col0 + 32 * dd + 8 * (g + h);
;             const u32x4 gq = *(const u32x4*)(G + off);
;             const auto s0 = __builtin_amdgcn_permlane32_swap(gq.x, gq.z, false, false);
;             const auto s1 = __builtin_amdgcn_permlane32_swap(gq.y, gq.w, false, false);
;             const unsigned gg[2] = {s0[0], s1[0]}, gh[2] = {s0[1], s1[1]};
;             f32x4 tg, th;
; #pragma unroll
;             for (int e = 0; e < 4; ++e) {
;                 const float og = (dd == 0 ? o0[4 * g + e] : o1[4 * g + e]), oh = (dd == 0 ? o0[4 * g + 4 + e] : o1[4 * g + 4 + e]);
;                 const unsigned wg = gg[e >> 1], wh = gh[e >> 1];
;                 tg[e] = og * inv * bf2f((unsigned short)((e & 1) ? (wg >> 16) : (wg & 0xffffu)));
;                 th[e] = oh * inv * bf2f((unsigned short)((e & 1) ? (wh >> 16) : (wh & 0xffffu)));
;             }
;             const u32x2 yg = __builtin_bit_cast(u32x2, pack4(tg)), yh = __builtin_bit_cast(u32x2, pack4(th));
;             const auto t0 = __builtin_amdgcn_permlane32_swap(yg.x, yh.x, false, false);
;             const auto t1 = __builtin_amdgcn_permlane32_swap(yg.y, yh.y, false, false);
;             *(u32x4*)(Y + off) = (u32x4){t0[0], t1[0], t0[1], t1[1]};
;         }
; }
; DI void attn_wgB_item(const bf16_t* Qm, const bf16_t* Km, const bf16_t* Vtm, const bf16_t* G, bf16_t* Y, int bh, int qb2, int halfq, LAS unsigned char* lds, int tid, int wave, int lane) {
;     ...
;     store_y(oA0, oA1, 1.0f, G, Y, (size_t)(bh >> 3) * S + tA, 1 * 512 + (bh & 7) * 64, h);
.LBB0_425:
	v_lshl_add_u64 v[2:3], v[108:109], 0, s[52:53]
	s_lshl_b32 s2, s64, 6
	s_bitset1_b32 s2, 9
	v_lshlrev_b64 v[2:3], 11, v[2:3]
	v_or_b32_e32 v2, s2, v2
	v_lshl_add_u64 v[4:5], v[2:3], 0, v[106:107]
	v_lshlrev_b64 v[8:9], 1, v[4:5]
	v_lshl_add_u64 v[4:5], s[84:85], 0, v[8:9]
	global_load_dwordx4 v[240:243], v[4:5], off offset:32
	global_load_dwordx4 v[244:247], v[4:5], off offset:64
	global_load_dwordx4 v[248:251], v[4:5], off offset:96
	global_load_dwordx4 v[4:7], v[4:5], off
	v_ashrrev_i32_e32 v105, 31, v104
	v_lshl_add_u64 v[10:11], v[2:3], 0, v[104:105]
	v_lshlrev_b64 v[10:11], 1, v[10:11]
	v_lshl_add_u64 v[8:9], s[94:95], 0, v[8:9]
	v_lshl_add_u64 v[12:13], s[84:85], 0, v[10:11]
	v_or_b32_e32 v2, 32, v2
	v_lshl_add_u64 v[10:11], s[94:95], 0, v[10:11]
	s_mov_b64 s[2:3], 0
	s_waitcnt vmcnt(0)
	v_mov_b32_e32 v0, v6
	v_mov_b32_e32 v49, v7
	s_nop 0
	v_permlane32_swap_b32_e32 v4, v0
	v_permlane32_swap_b32_e32 v5, v49
	v_lshlrev_b32_e32 v6, 16, v4
	v_lshlrev_b32_e32 v14, 16, v0
	v_and_b32_e32 v7, 0xffff0000, v4
	v_and_b32_e32 v15, 0xffff0000, v0
	v_lshlrev_b32_e32 v4, 16, v5
	v_lshlrev_b32_e32 v48, 16, v49
	v_and_b32_e32 v5, 0xffff0000, v5
	v_and_b32_e32 v49, 0xffff0000, v49
	v_pk_mul_f32 v[6:7], v[32:33], v[6:7]
	v_pk_mul_f32 v[14:15], v[36:37], v[14:15]
	v_pk_mul_f32 v[4:5], v[34:35], v[4:5]
	v_pk_mul_f32 v[32:33], v[38:39], v[48:49]
	v_cvt_pk_bf16_f32 v5, v4, v5
	v_cvt_pk_bf16_f32 v4, v6, v7
	v_cvt_pk_bf16_f32 v7, v32, v33
	v_cvt_pk_bf16_f32 v6, v14, v15
	s_nop 1
	v_permlane32_swap_b32_e32 v4, v6
	v_permlane32_swap_b32_e32 v5, v7
	global_store_dwordx4 v[8:9], v[4:7], off
	v_lshl_add_u64 v[8:9], v[2:3], 0, v[106:107]
	v_lshlrev_b64 v[8:9], 1, v[8:9]
	v_lshl_add_u64 v[12:13], s[84:85], 0, v[8:9]
	v_lshl_add_u64 v[2:3], v[2:3], 0, v[104:105]
	v_lshl_add_u64 v[8:9], s[94:95], 0, v[8:9]
	v_mov_b32_e32 v4, v240
	v_mov_b32_e32 v5, v241
	v_mov_b32_e32 v6, v242
	v_mov_b32_e32 v7, v243
	v_mov_b32_e32 v0, v6
	v_mov_b32_e32 v33, v7
	s_nop 0
	v_permlane32_swap_b32_e32 v4, v0
	v_permlane32_swap_b32_e32 v5, v33
	v_lshlrev_b32_e32 v6, 16, v4
	v_lshlrev_b32_e32 v14, 16, v0
	v_and_b32_e32 v7, 0xffff0000, v4
	v_and_b32_e32 v15, 0xffff0000, v0
	v_lshlrev_b32_e32 v4, 16, v5
	v_lshlrev_b32_e32 v32, 16, v33
	v_and_b32_e32 v5, 0xffff0000, v5
	v_and_b32_e32 v33, 0xffff0000, v33
	v_pk_mul_f32 v[6:7], v[40:41], v[6:7]
	v_pk_mul_f32 v[14:15], v[44:45], v[14:15]
	v_pk_mul_f32 v[4:5], v[42:43], v[4:5]
	v_pk_mul_f32 v[32:33], v[46:47], v[32:33]
	v_cvt_pk_bf16_f32 v5, v4, v5
	v_cvt_pk_bf16_f32 v4, v6, v7
	v_cvt_pk_bf16_f32 v7, v32, v33
	v_cvt_pk_bf16_f32 v6, v14, v15
	s_nop 1
	v_permlane32_swap_b32_e32 v4, v6
	v_permlane32_swap_b32_e32 v5, v7
	global_store_dwordx4 v[10:11], v[4:7], off
	v_lshlrev_b64 v[10:11], 1, v[2:3]
	v_lshl_add_u64 v[12:13], s[84:85], 0, v[10:11]
	v_mov_b32_e32 v4, v244
	v_mov_b32_e32 v5, v245
	v_mov_b32_e32 v6, v246
	v_mov_b32_e32 v7, v247
	v_mov_b32_e32 v0, v6
	v_mov_b32_e32 v15, v7
	s_nop 0
	v_permlane32_swap_b32_e32 v4, v0
	v_permlane32_swap_b32_e32 v5, v15
	v_lshlrev_b32_e32 v2, 16, v4
	v_lshlrev_b32_e32 v6, 16, v0
	v_and_b32_e32 v3, 0xffff0000, v4
	v_and_b32_e32 v7, 0xffff0000, v0
	v_lshlrev_b32_e32 v4, 16, v5
	v_lshlrev_b32_e32 v14, 16, v15
	v_and_b32_e32 v5, 0xffff0000, v5
	v_and_b32_e32 v15, 0xffff0000, v15
	v_pk_mul_f32 v[16:17], v[16:17], v[2:3]
	v_pk_mul_f32 v[6:7], v[20:21], v[6:7]
	v_pk_mul_f32 v[2:3], v[18:19], v[4:5]
	v_pk_mul_f32 v[4:5], v[22:23], v[14:15]
	v_cvt_pk_bf16_f32 v3, v2, v3
	v_cvt_pk_bf16_f32 v2, v16, v17
	v_cvt_pk_bf16_f32 v5, v4, v5
	v_cvt_pk_bf16_f32 v4, v6, v7
	s_nop 1
	v_permlane32_swap_b32_e32 v2, v4
	v_permlane32_swap_b32_e32 v3, v5
	global_store_dwordx4 v[8:9], v[2:5], off
	v_lshl_add_u64 v[6:7], s[94:95], 0, v[10:11]
	s_nop 1
	v_mov_b32_e32 v2, v248
	v_mov_b32_e32 v3, v249
	v_mov_b32_e32 v4, v250
	v_mov_b32_e32 v5, v251
	v_mov_b32_e32 v0, v4
	v_mov_b32_e32 v9, v5
	s_nop 0
	v_permlane32_swap_b32_e32 v2, v0
	v_permlane32_swap_b32_e32 v3, v9
	v_lshlrev_b32_e32 v4, 16, v0
	v_and_b32_e32 v5, 0xffff0000, v0
	v_lshlrev_b32_e32 v8, 16, v9
	v_lshlrev_b32_e32 v10, 16, v2
	v_and_b32_e32 v11, 0xffff0000, v2
	v_lshlrev_b32_e32 v2, 16, v3
	v_and_b32_e32 v3, 0xffff0000, v3
	v_and_b32_e32 v9, 0xffff0000, v9
	v_pk_mul_f32 v[12:13], v[28:29], v[4:5]
	v_pk_mul_f32 v[4:5], v[24:25], v[10:11]
	v_pk_mul_f32 v[2:3], v[26:27], v[2:3]
	v_pk_mul_f32 v[8:9], v[30:31], v[8:9]
	v_cvt_pk_bf16_f32 v3, v2, v3
	v_cvt_pk_bf16_f32 v2, v4, v5
	v_cvt_pk_bf16_f32 v5, v8, v9
	v_cvt_pk_bf16_f32 v4, v12, v13
	s_nop 1
	v_permlane32_swap_b32_e32 v2, v4
	v_permlane32_swap_b32_e32 v3, v5
	global_store_dwordx4 v[6:7], v[2:5], off
